# SSM table build: B/C parameter loads (4 dependent HBM round trips) hoisted to the phase start
# baseline (speedup 1.0000x reference)
; __device__ void phase_ssm(int j, unsigned char* lds) {
;     ...
;         { const bf16_t* usrc = UG + (size_t)g * GSTR;
; #pragma unroll
;           for (int it = 0; it < 4; ++it) pf[it] = *(const u32x4*)(usrc + (size_t)(tid + NTHREADS * it) * 8); }
;         { f32x4* TMP = (f32x4*)(lds + L_UBUF);
;           if (tid < 64) { const int n = tid;
;             const float are = pq->in[8][((size_t)j * NG + g) * NS + n], aim = pq->in[9][((size_t)j * NG + g) * NS + n];
;             const float dt = expf(pq->in[10][(size_t)j * NG + g]);
;             const float mag = expf(are * dt); float sn, cs; sincosf(aim * dt, &sn, &cs);
;             const float abr = mag * cs, abi = mag * sn, den = are * are + aim * aim, nr = abr - 1.0f;
;             TMP[n] = (f32x4){are * dt, aim * dt, (nr * are + abi * aim) / den, (abi * are - nr * aim) / den}; }
;           __syncthreads();
;           for (int i = tid; i < 64 * 17; i += NTHREADS) { const int n = i / 17, k = i - n * 17; const f32x4 t4 = TMP[n];
;               const float mg = expf(t4[0] * (float)k); float sn, cs; sincosf(t4[1] * (float)k, &sn, &cs); APOW[i] = (f32x2){mg * cs, mg * sn}; }
;           for (int i = tid; i < NS * NP; i += NTHREADS) { const int n = i >> 4; const f32x4 t4 = TMP[n]; const size_t o = ((size_t)j * NG + g) * NS * NP + i;
;               const float bre = pq->in[11][o], bim = pq->in[12][o]; BBAR[n * 17 + (i & 15)] = (f32x2){t4[2] * bre - t4[3] * bim, t4[2] * bim + t4[3] * bre}; }
;           for (int i = tid; i < NP * NS; i += NTHREADS) { const size_t o = ((size_t)j * NG + g) * NP * NS + i; CC[(i >> 6) * 65 + (i & 63)] = (f32x2){pq->in[13][o], pq->in[14][o]}; }
.LBB0_691:
	s_mul_hi_i32 s1, s22, 0x20880
	s_mul_i32 s0, s22, 0x20880
	s_ashr_i32 s23, s22, 31
	s_lshl_b64 s[0:1], s[0:1], 1
	v_readlane_b32 s4, v254, 58
	s_add_u32 s38, s4, s0
	v_readlane_b32 s4, v254, 59
	s_addc_u32 s39, s4, s1
	v_lshl_add_u64 v[2:3], s[38:39], 0, v[136:137]
	s_barrier
	v_lshl_add_u64 v[4:5], s[38:39], 0, v[138:139]
	global_load_dwordx4 v[18:21], v[2:3], off
	global_load_dwordx4 v[22:25], v[4:5], off
	v_lshl_add_u64 v[2:3], s[38:39], 0, v[140:141]
	v_lshl_add_u64 v[4:5], s[38:39], 0, v[142:143]
	global_load_dwordx4 v[26:29], v[2:3], off
	global_load_dwordx4 v[30:33], v[4:5], off
	s_load_dwordx4 s[96:99], s[36:37], 0x58
	s_lshl_b64 s[24:25], s[22:23], 10
	v_lshl_add_u64 v[40:41], v[148:149], 0, s[24:25]
	v_lshlrev_b64 v[40:41], 2, v[40:41]
	s_waitcnt lgkmcnt(0)
	v_lshl_add_u64 v[42:43], s[96:97], 0, v[40:41]
	v_lshl_add_u64 v[44:45], s[98:99], 0, v[40:41]
	global_load_dword v46, v[42:43], off
	global_load_dword v47, v[44:45], off
	global_load_dword v48, v[42:43], off offset:2048
	global_load_dword v49, v[44:45], off offset:2048
	s_load_dwordx4 s[96:99], s[36:37], 0x68
	s_waitcnt lgkmcnt(0)
	v_lshl_add_u64 v[42:43], s[96:97], 0, v[40:41]
	v_lshl_add_u64 v[44:45], s[98:99], 0, v[40:41]
	global_load_dword v50, v[42:43], off
	global_load_dword v51, v[44:45], off
	global_load_dword v52, v[42:43], off offset:2048
	global_load_dword v53, v[44:45], off offset:2048
	s_mov_b64 s[4:5], exec
	v_readlane_b32 s24, v254, 62
	v_readlane_b32 s25, v254, 63
	s_and_b64 s[24:25], s[4:5], s[24:25]
	s_mov_b64 exec, s[24:25]
	s_cbranch_execz .LBB0_697
	s_load_dwordx2 s[24:25], s[36:37], 0x50
	s_load_dwordx4 s[96:99], s[36:37], 0x40
	v_readlane_b32 s34, v252, 0
	v_readlane_b32 s35, v252, 1
	s_add_u32 s34, s34, s22
	s_addc_u32 s35, s35, s23
	s_lshl_b64 s[94:95], s[34:35], 6
	s_lshl_b64 s[34:35], s[34:35], 2
	s_waitcnt lgkmcnt(0)
	s_add_u32 s24, s24, s34
	s_addc_u32 s25, s25, s35
	global_load_dword v0, v1, s[24:25]
	v_lshl_add_u64 v[2:3], s[94:95], 0, v[134:135]
	v_lshlrev_b64 v[2:3], 2, v[2:3]
	v_lshl_add_u64 v[4:5], s[96:97], 0, v[2:3]
	v_lshl_add_u64 v[2:3], s[98:99], 0, v[2:3]
	global_load_dword v4, v[4:5], off
	s_nop 0
	global_load_dword v5, v[2:3], off
	s_mov_b32 s24, 0x3fb8aa3b
	s_waitcnt vmcnt(2)
	v_mul_f32_e32 v2, 0x3fb8aa3b, v0
	v_fma_f32 v3, v0, s24, -v2
	v_rndne_f32_e32 v6, v2
	v_fmac_f32_e32 v3, 0x32a5705f, v0
	v_sub_f32_e32 v2, v2, v6
	v_add_f32_e32 v2, v2, v3
	v_cvt_i32_f32_e32 v6, v6
	v_exp_f32_e32 v2, v2
	s_mov_b32 s24, 0xc2ce8ed0
	v_cmp_ngt_f32_e32 vcc, s24, v0
	s_mov_b32 s24, 0x42b17218
	v_ldexp_f32 v2, v2, v6
	v_cndmask_b32_e32 v2, 0, v2, vcc
	v_cmp_nlt_f32_e32 vcc, s24, v0
	s_brev_b32 s24, 18
	s_nop 0
	v_cndmask_b32_e32 v0, v239, v2, vcc
	s_waitcnt vmcnt(0)
	v_pk_mul_f32 v[2:3], v[4:5], v[0:1] op_sel_hi:[1,0]
	s_nop 0
	v_and_b32_e32 v6, 0x7fffffff, v3
	v_cmp_nlt_f32_e64 s[24:25], |v3|, s24
	s_and_saveexec_b64 s[34:35], s[24:25]
	s_xor_b64 s[24:25], exec, s[34:35]
	s_cbranch_execz .LBB0_694
	v_lshrrev_b32_e32 v0, 23, v6
	v_add_u32_e32 v0, 0xffffff88, v0
	v_cmp_lt_u32_e32 vcc, 63, v0
	s_mov_b32 s34, 0xfe5163ab
	s_nop 0
	v_cndmask_b32_e32 v7, 0, v240, vcc
	v_add_u32_e32 v0, v7, v0
	v_cmp_lt_u32_e64 s[94:95], 31, v0
	s_nop 1
	v_cndmask_b32_e64 v7, 0, v241, s[94:95]
	v_add_u32_e32 v0, v7, v0
	v_cmp_lt_u32_e64 s[96:97], 31, v0
	s_nop 1
	v_cndmask_b32_e64 v7, 0, v241, s[96:97]
	v_add_u32_e32 v7, v7, v0
	v_and_b32_e32 v0, 0x7fffff, v6
	v_or_b32_e32 v36, 0x800000, v0
	v_mad_u64_u32 v[8:9], s[34:35], v36, s34, 0
	v_mov_b32_e32 v0, v9
	s_mov_b32 s34, 0x3c439041
	v_mad_u64_u32 v[10:11], s[34:35], v36, s34, v[0:1]
	v_mov_b32_e32 v0, v11
	s_mov_b32 s34, 0xdb629599
	v_mad_u64_u32 v[12:13], s[34:35], v36, s34, v[0:1]
	v_mov_b32_e32 v0, v13
	s_mov_b32 s34, 0xf534ddc0
	v_mad_u64_u32 v[14:15], s[34:35], v36, s34, v[0:1]
	v_mov_b32_e32 v0, v15
	s_mov_b32 s34, 0xfc2757d1
	v_mad_u64_u32 v[16:17], s[34:35], v36, s34, v[0:1]
	v_mov_b32_e32 v0, v17
	s_mov_b32 s34, 0x4e441529
	v_mad_u64_u32 v[34:35], s[34:35], v36, s34, v[0:1]
	v_mov_b32_e32 v0, v35
	s_mov_b32 s34, 0xa2f9836e
	v_mad_u64_u32 v[36:37], s[34:35], v36, s34, v[0:1]
	v_cndmask_b32_e32 v9, v34, v14, vcc
	v_cndmask_b32_e32 v0, v36, v16, vcc
	v_cndmask_b32_e32 v13, v37, v34, vcc
	v_cndmask_b32_e64 v11, v0, v9, s[94:95]
	v_cndmask_b32_e64 v0, v13, v0, s[94:95]
	v_cndmask_b32_e32 v13, v16, v12, vcc
	v_cndmask_b32_e64 v9, v9, v13, s[94:95]
	v_cndmask_b32_e64 v0, v0, v11, s[96:97]
	v_cndmask_b32_e64 v11, v11, v9, s[96:97]
	v_sub_u32_e32 v15, 32, v7
	v_alignbit_b32 v16, v0, v11, v15
	v_cmp_eq_u32_e64 s[98:99], 0, v7
	v_cndmask_b32_e32 v8, v12, v8, vcc
	s_mov_b32 s34, 0x3fc90fda
	v_cndmask_b32_e64 v7, v16, v0, s[98:99]
	v_cndmask_b32_e32 v0, v14, v10, vcc
	v_cndmask_b32_e64 v10, v13, v0, s[94:95]
	v_cndmask_b32_e64 v9, v9, v10, s[96:97]
	v_alignbit_b32 v13, v11, v9, v15
	v_cndmask_b32_e64 v11, v13, v11, s[98:99]
	v_bfe_u32 v16, v7, 29, 1
	v_cndmask_b32_e64 v0, v0, v8, s[94:95]
	v_alignbit_b32 v13, v7, v11, 30
	v_sub_u32_e32 v17, 0, v16
	v_cndmask_b32_e64 v0, v10, v0, s[96:97]
	v_xor_b32_e32 v13, v13, v17
	v_alignbit_b32 v8, v9, v0, v15
	v_cndmask_b32_e64 v8, v8, v9, s[98:99]
	v_ffbh_u32_e32 v10, v13
	v_alignbit_b32 v9, v11, v8, 30
	v_min_u32_e32 v10, 32, v10
	v_alignbit_b32 v0, v8, v0, 30
	v_xor_b32_e32 v9, v9, v17
	v_sub_u32_e32 v11, 31, v10
	v_xor_b32_e32 v0, v0, v17
	v_alignbit_b32 v12, v13, v9, v11
	v_alignbit_b32 v0, v9, v0, v11
	v_alignbit_b32 v8, v12, v0, 9
	v_ffbh_u32_e32 v9, v8
	v_min_u32_e32 v9, 32, v9
	v_lshrrev_b32_e32 v14, 29, v7
	v_not_b32_e32 v11, v9
	v_alignbit_b32 v0, v8, v0, v11
	v_lshlrev_b32_e32 v8, 31, v14
	v_or_b32_e32 v11, 0x33000000, v8
	v_add_lshl_u32 v9, v9, v10, 23
	v_lshrrev_b32_e32 v0, 9, v0
	v_sub_u32_e32 v9, v11, v9
	v_or_b32_e32 v8, 0.5, v8
	v_lshlrev_b32_e32 v10, 23, v10
	v_or_b32_e32 v0, v9, v0
	v_lshrrev_b32_e32 v9, 9, v12
	v_sub_u32_e32 v8, v8, v10
	v_or_b32_e32 v8, v9, v8
	v_mul_f32_e32 v9, 0x3fc90fda, v8
	v_fma_f32 v10, v8, s34, -v9
	v_fmac_f32_e32 v10, 0x33a22168, v8
	v_fmac_f32_e32 v10, 0x3fc90fda, v0
	v_lshrrev_b32_e32 v7, 30, v7
	v_add_f32_e32 v0, v9, v10
	v_add_u32_e32 v7, v16, v7

; __device__ void phase_ssm(int j, unsigned char* lds) {
;     ...
;           for (int i = tid; i < NS * NP; i += NTHREADS) { const int n = i >> 4; const f32x4 t4 = TMP[n]; const size_t o = ((size_t)j * NG + g) * NS * NP + i;
;               const float bre = pq->in[11][o], bim = pq->in[12][o]; BBAR[n * 17 + (i & 15)] = (f32x2){t4[2] * bre - t4[3] * bim, t4[2] * bim + t4[3] * bre}; }
;           for (int i = tid; i < NP * NS; i += NTHREADS) { const size_t o = ((size_t)j * NG + g) * NP * NS + i; CC[(i >> 6) * 65 + (i & 63)] = (f32x2){pq->in[13][o], pq->in[14][o]}; }
.LBB0_704:
	s_or_b64 exec, exec, s[4:5]
	s_and_saveexec_b64 s[4:5], s[44:45]
	s_mov_b32 s94, 0x41100
	s_movk_i32 s95, 0x208
	s_cbranch_execz .LBB0_709
	s_mov_b64 s[24:25], 0
	s_waitcnt lgkmcnt(0)
	v_mov_b32_e32 v0, v134
	s_movk_i32 s23, 0x88
.LBB0_706:
	v_and_b32_e32 v8, -16, v0
	v_add_u32_e32 v9, 0, v8
	v_mov_b32_e32 v8, v46
	v_mov_b32_e32 v10, v47
	ds_read_b64 v[12:13], v9 offset:46216
	v_ashrrev_i32_e32 v16, 4, v0
	v_cmp_lt_i32_e32 vcc, s33, v0
	s_or_b64 s[24:25], vcc, s[24:25]
	s_waitcnt vmcnt(0) lgkmcnt(0)
	v_pk_mul_f32 v[10:11], v[12:13], v[10:11] op_sel:[1,0] op_sel_hi:[0,0]
	v_pk_fma_f32 v[14:15], v[12:13], v[8:9], v[10:11] neg_lo:[0,0,1] neg_hi:[0,0,1]
	v_pk_fma_f32 v[8:9], v[12:13], v[8:9], v[10:11] op_sel_hi:[1,0,1]
	s_nop 0
	v_mov_b32_e32 v15, v9
	v_mad_u64_u32 v[8:9], s[34:35], v16, s23, v[144:145]
	ds_write_b64 v8, v[14:15] offset:8704
	v_add_u32_e32 v8, 0x200, v0
	v_mov_b32_e32 v0, v8
	s_andn2_b64 exec, exec, s[24:25]
	v_mov_b32_e32 v46, v48
	v_mov_b32_e32 v47, v49
	s_cbranch_execnz .LBB0_706
	s_or_b64 exec, exec, s[24:25]
	s_mov_b64 s[24:25], 0
	v_mov_b32_e32 v0, v134
	s_waitcnt lgkmcnt(0)
.LBB0_708:
	v_mov_b32_e32 v6, v50
	v_mov_b32_e32 v7, v51
	v_ashrrev_i32_e32 v8, 6, v0
	v_mad_u64_u32 v[8:9], s[34:35], v8, s95, v[146:147]
	v_cmp_lt_i32_e32 vcc, s33, v0
	s_or_b64 s[24:25], vcc, s[24:25]
	s_waitcnt vmcnt(0)
	ds_write_b64 v8, v[6:7] offset:17408
	v_add_u32_e32 v6, 0x200, v0
	v_mov_b32_e32 v0, v6
	s_andn2_b64 exec, exec, s[24:25]
	v_mov_b32_e32 v50, v52
	v_mov_b32_e32 v51, v53
	s_cbranch_execnz .LBB0_708
